# lru1/lru2: conv weights staged once in LDS (ds_read instead of 10 L2 loads per tile); lru2 z-gate loads left in flight past the conv
# speedup vs baseline: 1.0075x; 1.0075x over previous
; __device__ __forceinline__ float softplusf_(float x) { return fmaxf(x, 0.f) + log1pf(__expf(-fabsf(x))); }
; template <int PASS> __device__ void lru_phase(const Params& p, unsigned char* smem) {
;     float* xcf = (float*)smem;
;     float* As = xcf + 64 * 132;
;     float* Us = As + 64 * 132;
;     float* qA = Us + 64 * 132;
;     float* qH = qA + 512;
;     const int tid = threadIdx.x, lane = tid & 63, wave = __builtin_amdgcn_readfirstlane(tid >> 6);
;     const u16* XR = (const u16*)(p.ws + OFF_XR);
;     u16* Y0 = (u16*)(p.ws + OFF_Y0);
;     const u16* LW = (const u16*)(p.ws + OFF_LRUW);
;     float* LA = (float*)(p.ws + OFF_LRUA); float* LH = (float*)(p.ws + OFF_LRUH); const float* LC = (const float*)(p.ws + OFF_LRUC);
;     const float* cw = p.in[3]; const float* cb = p.in[4];
;     u32x4 craw[2][4];
;     ...
;     if ((int)blockIdx.x < 4096) LRU_CLOAD((int)blockIdx.x);
;     const bool jb_fixed = (gridDim.x & 15) == 0;
;     bf16x8 hba[4], hbx[4]; float hb_a = 0.f, hb_x = 0.f, hsp = 0.f;
;     if (jb_fixed) { const int jb0 = blockIdx.x & 15, cg0 = jb0 * 128 + 16 * wave + (lane & 15);
; #pragma unroll
;         for (int ks = 0; ks < 4; ++ks) { const size_t wo = (size_t)((jb0 * 128 + 16 * wave + (lane & 15)) * 128 + ks * 32 + 8 * (lane >> 4));
;             hba[ks] = *(const bf16x8*)(LW + wo); hbx[ks] = *(const bf16x8*)(LW + (size_t)16 * 128 * 128 + wo); }
;         hb_a = p.in[6][cg0]; hb_x = p.in[8][cg0]; hsp = softplusf_(-p.in[9][cg0]); }
;     for (int tile = blockIdx.x; tile < 4096; tile += gridDim.x) {
.LBB0_323:
	s_add_u32 s12, s64, 0x1f100000
	s_addc_u32 s13, s65, 0
	s_add_u32 s14, s64, 0x1f300000
	v_lshrrev_b32_e32 v70, 2, v1
	s_addc_u32 s15, s65, 0
	v_and_b32_e32 v67, 15, v1
	v_and_b32_e32 v70, 12, v70
	s_add_u32 s16, s64, 0x1f780000
	v_lshl_or_b32 v132, s4, 4, v67
	v_lshrrev_b32_e32 v72, 3, v1
	v_lshlrev_b32_e32 v76, 7, v67
	v_mul_u32_u24_e32 v77, 0x210, v67
	v_mul_u32_u24_e32 v67, 0x84, v70
	s_addc_u32 s17, s65, 0
	v_and_b32_e32 v73, 0x70, v72
	v_add_lshl_u32 v67, v132, v67, 2
	s_add_i32 s19, 0, 0x10800
	v_and_b32_e32 v71, 0x7f, v1
	v_add_u32_e32 v135, 0, v67
	v_add_u32_e32 v136, s19, v67
	v_mul_u32_u24_e32 v67, 0x84, v73
	v_add_lshl_u32 v67, v67, v71, 2
	v_add_u32_e32 v152, 0, v67
	v_add_u32_e32 v153, s19, v67
	v_or_b32_e32 v67, 15, v72
	v_mul_u32_u24_e32 v67, 0x84, v67
	v_lshlrev_b32_e32 v74, 2, v1
	v_add_lshl_u32 v67, v67, v71, 2
	v_lshlrev_b32_e32 v66, 3, v1
	v_lshrrev_b32_e32 v68, 1, v1
	s_add_i32 s5, 0, 0x18c00
	s_add_i32 s18, 0, 0x19400
	v_add_u32_e32 v168, 0, v67
	v_add_u32_e32 v169, s19, v67
	v_or_b32_e32 v67, 0x200, v74
	v_lshrrev_b32_e32 v129, 4, v1
	v_and_b32_e32 v130, 0x78, v66
	v_and_b32_e32 v68, 24, v68
	s_lshl_b32 s4, s4, 11
	v_add_u32_e32 v170, s5, v67
	v_add_u32_e32 v171, s18, v67
	v_or_b32_e32 v67, 0x400, v74
	v_lshl_add_u32 v66, v130, 2, 0
	v_lshl_add_u32 v69, v68, 2, 0
	s_movk_i32 s2, 0x80
	v_mul_u32_u24_e32 v75, 0x210, v129
	v_add_u32_e32 v172, s5, v67
	v_add_u32_e32 v173, s18, v67
	v_or_b32_e32 v67, 0x600, v74
	v_or3_b32 v176, s4, v76, v68
	s_add_i32 s4, s70, s62
	v_add_u32_e32 v131, -3, v129
	v_add_u32_e32 v133, s5, v74
	v_add_u32_e32 v134, s18, v74
	v_cmp_gt_u32_e64 s[2:3], s2, v1
	v_add_u32_e32 v137, 0x210, v136
	v_add_u32_e32 v138, 0x420, v136
	v_add_u32_e32 v139, 0x630, v136
	v_add_u32_e32 v140, 0x2100, v136
	v_add_u32_e32 v141, 0x2310, v136
	v_add_u32_e32 v142, 0x2520, v136
	v_add_u32_e32 v143, 0x2730, v136
	v_add_u32_e32 v144, 0x4200, v136
	v_add_u32_e32 v145, 0x4410, v136
	v_add_u32_e32 v146, 0x4620, v136
	v_add_u32_e32 v147, 0x4830, v136
	v_add_u32_e32 v148, 0x6300, v136
	v_add_u32_e32 v149, 0x6510, v136
	v_add_u32_e32 v150, 0x6720, v136
	v_add_u32_e32 v151, 0x6930, v136
	v_add_u32_e32 v154, 0x210, v153
	v_add_u32_e32 v155, 0x420, v153
	v_add_u32_e32 v156, 0x630, v153
	v_add_u32_e32 v157, 0x840, v153
	v_add_u32_e32 v158, 0xa50, v153
	v_add_u32_e32 v159, 0xc60, v153
	v_add_u32_e32 v160, 0xe70, v153
	v_add_u32_e32 v161, 0x1080, v153
	v_add_u32_e32 v162, 0x1290, v153
	v_add_u32_e32 v163, 0x14a0, v153
	v_add_u32_e32 v164, 0x16b0, v153
	v_add_u32_e32 v165, 0x18c0, v153
	v_add_u32_e32 v166, 0x1ad0, v153
	v_add_u32_e32 v167, 0x1ce0, v153
	v_add_u32_e32 v174, s5, v67
	v_add_u32_e32 v175, s18, v67
	s_lshl_b32 s26, s4, 7
	s_lshl_b32 s27, s62, 7
	s_lshl_b32 s28, s4, 2
	s_lshl_b32 s29, s62, 2
	v_mov_b32_e32 v67, 0
	s_mov_b64 s[18:19], 0x2000
	s_movk_i32 s30, 0x2000
	s_mov_b64 s[20:21], 0x4000
	s_movk_i32 s31, 0x4000
	s_mov_b64 s[22:23], 0x6000
	s_movk_i32 s33, 0x6000
	v_add_u32_e32 v177, v66, v75
	s_mov_b32 s34, 0xbfb8aa3b
	s_mov_b32 s35, 0x3f2aaaab
	v_mov_b32_e32 v178, 0x3ecc95a3
	s_mov_b32 s36, 0x3f317218
	s_mov_b32 s37, 0x7f800000
	s_mov_b32 s38, 0x33800000
	v_add_u32_e32 v179, v69, v77
	v_mov_b32_e32 v124, 0x3f317218
	v_mov_b32_e32 v180, 0x7f800000
	v_mov_b32_e32 v181, 0x7fc00000
	v_mov_b32_e32 v182, 0xff800000
	s_mov_b32 s39, s70
	s_mov_b32 s60, 0
	s_branch .LBB0_325

; __device__ __forceinline__ void unpack8(u32x4 w, float* f) { f[0] = bflo(w.x); f[1] = bfhi(w.x); f[2] = bflo(w.y); f[3] = bfhi(w.y); f[4] = bflo(w.z); f[5] = bfhi(w.z); f[6] = bflo(w.w); f[7] = bfhi(w.w); }
; template <int PASS> __device__ void lru_phase(const Params& p, unsigned char* smem) {
;     ...
;             { const f32x4 b0 = *(const f32x4*)(cb + ch), b1 = *(const f32x4*)(cb + ch + 4);
; #pragma unroll
;               for (int i = 0; i < 4; ++i) { acc[i] = b0[i]; acc[4 + i] = b1[i]; } }
; #pragma unroll
;             for (int j = 0; j < 4; ++j) { float xv[8]; unpack8(craw[it][j], xv);
;                 const f32x4 w0 = *(const f32x4*)(cw + j * 2048 + ch), w1 = *(const f32x4*)(cw + j * 2048 + ch + 4);
.LBB0_325:
	s_cmp_eq_u32 s60, 0
	s_cselect_b64 vcc, -1, s[10:11]
	s_mov_b32 s60, 1
	s_cbranch_vccz LRUW1_staged
	v_readlane_b32 s76, v251, 2
	v_readlane_b32 s77, v251, 3
	v_readlane_b32 s78, v251, 4
	v_readlane_b32 s79, v251, 5
	s_and_b32 s61, s39, 15
	s_lshl_b32 s61, s61, 9
	v_and_b32_e32 v248, 0x3ff, v0
	v_and_b32_e32 v249, 15, v248
	v_lshlrev_b32_e32 v249, 5, v249
	v_add_u32_e32 v249, 0x1a000, v249
	v_cmp_gt_u32_e32 vcc, 0xa0, v248
	s_and_saveexec_b64 s[82:83], vcc
	s_cbranch_execz LRUW1_nost
	v_lshrrev_b32_e32 v247, 5, v248
	v_and_b32_e32 v246, 31, v248
	v_lshlrev_b32_e32 v246, 4, v246
	v_add_u32_e32 v246, s61, v246
	v_cmp_eq_u32_e32 vcc, 4, v247
	v_lshlrev_b32_e32 v247, 13, v247
	v_add_u32_e32 v247, v247, v246
	v_cndmask_b32_e32 v247, v247, v246, vcc
	v_mov_b32_e32 v244, s76
	v_mov_b32_e32 v245, s77
	v_mov_b32_e32 v242, s78
	v_mov_b32_e32 v243, s79
	v_cndmask_b32_e32 v244, v244, v242, vcc
	v_cndmask_b32_e32 v245, v245, v243, vcc
	v_add_co_u32_e32 v244, vcc, v244, v247
	s_nop 1
	v_addc_co_u32_e32 v245, vcc, 0, v245, vcc
	global_load_dwordx4 v[236:239], v[244:245], off
	v_lshlrev_b32_e32 v246, 4, v248
	v_add_u32_e32 v246, 0x1a000, v246
	s_waitcnt vmcnt(0)
	ds_write_b128 v246, v[236:239]
LRUW1_nost:
	s_or_b64 exec, exec, s[82:83]
	s_waitcnt lgkmcnt(0)
	s_barrier
; __device__ __forceinline__ void unpack8(u32x4 w, float* f) { f[0] = bflo(w.x); f[1] = bfhi(w.x); f[2] = bflo(w.y); f[3] = bfhi(w.y); f[4] = bflo(w.z); f[5] = bfhi(w.z); f[6] = bflo(w.w); f[7] = bfhi(w.w); }
; template <int PASS> __device__ void lru_phase(const Params& p, unsigned char* smem) {
;     ...
;         for (int it = 0; it < 2; ++it) {
;             const int t = (tid >> 4) + 32 * it, c8 = (tid & 15) * 8, ch = jb * 128 + c8;
;             float acc[8];
;             { const f32x4 b0 = *(const f32x4*)(cb + ch), b1 = *(const f32x4*)(cb + ch + 4);
; #pragma unroll
;               for (int i = 0; i < 4; ++i) { acc[i] = b0[i]; acc[4 + i] = b1[i]; } }
; #pragma unroll
;             for (int j = 0; j < 4; ++j) { float xv[8]; unpack8(craw[it][j], xv);
;                 const f32x4 w0 = *(const f32x4*)(cw + j * 2048 + ch), w1 = *(const f32x4*)(cw + j * 2048 + ch + 4);
; #pragma unroll
;                 for (int i = 0; i < 4; ++i) { acc[i] += w0[i] * xv[i]; acc[4 + i] += w1[i] * xv[4 + i]; } }
;             *(f32x4*)(xcf + t * 132 + c8) = (f32x4){acc[0], acc[1], acc[2], acc[3]}; *(f32x4*)(xcf + t * 132 + c8 + 4) = (f32x4){acc[4], acc[5], acc[6], acc[7]};
;         }
LRUW1_staged:
	s_and_b32 s42, s39, 15
	s_lshl_b32 s40, s42, 7
	v_or_b32_e32 v66, s40, v130
	v_readlane_b32 s44, v251, 0
	v_lshlrev_b32_e32 v66, 2, v66
	v_readlane_b32 s46, v251, 2
	v_readlane_b32 s47, v251, 3
	v_readlane_b32 s48, v251, 4
	v_readlane_b32 s49, v251, 5
	v_lshl_add_u64 v[100:101], s[46:47], 0, v[66:67]
	v_add_co_u32_e32 v84, vcc, s30, v100
	s_nop 2
	ds_read_b128 v[68:71], v249 offset:2064
	ds_read_b128 v[72:75], v249 offset:16
	ds_read_b128 v[76:79], v249 offset:2048
	ds_read_b128 v[80:83], v249
	v_addc_co_u32_e32 v85, vcc, 0, v101, vcc
	v_add_co_u32_e32 v92, vcc, s31, v100
	v_lshl_add_u64 v[88:89], v[100:101], 0, s[18:19]
	s_nop 0
	v_addc_co_u32_e32 v93, vcc, 0, v101, vcc
	ds_read_b128 v[84:87], v249 offset:512
	s_nop 0
	ds_read_b128 v[88:91], v249 offset:528
	v_lshl_add_u64 v[96:97], v[100:101], 0, s[20:21]
	v_lshl_add_u64 v[104:105], v[100:101], 0, s[22:23]
	v_add_co_u32_e32 v100, vcc, s33, v100
	ds_read_b128 v[92:95], v249 offset:1024
	s_nop 0
	ds_read_b128 v[96:99], v249 offset:1040
	v_addc_co_u32_e32 v101, vcc, 0, v101, vcc
	ds_read_b128 v[100:103], v249 offset:1536
	s_nop 0
	ds_read_b128 v[104:107], v249 offset:1552
	s_waitcnt vmcnt(0) lgkmcnt(0)
	v_lshlrev_b32_e32 v108, 16, v6
	v_and_b32_e32 v109, 0xffff0000, v6
	v_lshlrev_b32_e32 v110, 16, v2
	v_and_b32_e32 v111, 0xffff0000, v2
	v_lshlrev_b32_e32 v116, 16, v8
	v_and_b32_e32 v117, 0xffff0000, v8
	v_lshlrev_b32_e32 v200, 16, v18
	v_and_b32_e32 v201, 0xffff0000, v18
	v_lshlrev_b32_e32 v112, 16, v10
	v_and_b32_e32 v113, 0xffff0000, v10
	v_lshlrev_b32_e32 v118, 16, v4
	v_and_b32_e32 v119, 0xffff0000, v4
	v_lshlrev_b32_e32 v114, 16, v14
	v_and_b32_e32 v115, 0xffff0000, v14
	v_lshlrev_b32_e32 v120, 16, v12
	v_and_b32_e32 v121, 0xffff0000, v12
	v_lshlrev_b32_e32 v202, 16, v22
	v_and_b32_e32 v203, 0xffff0000, v22
	v_lshlrev_b32_e32 v184, 16, v7
	v_and_b32_e32 v185, 0xffff0000, v7
	v_lshlrev_b32_e32 v186, 16, v3
	v_and_b32_e32 v187, 0xffff0000, v3
	v_lshlrev_b32_e32 v192, 16, v9
	v_and_b32_e32 v193, 0xffff0000, v9
	s_add_i32 s41, s39, s62
	v_lshlrev_b32_e32 v188, 16, v11
	v_and_b32_e32 v189, 0xffff0000, v11
	v_lshlrev_b32_e32 v194, 16, v5
	v_and_b32_e32 v195, 0xffff0000, v5
	v_lshlrev_b32_e32 v204, 16, v26
	v_and_b32_e32 v205, 0xffff0000, v26
	s_cmpk_gt_i32 s41, 0xfff
	v_lshlrev_b32_e32 v190, 16, v15
	v_and_b32_e32 v191, 0xffff0000, v15
	v_lshlrev_b32_e32 v196, 16, v13
	v_and_b32_e32 v197, 0xffff0000, v13
	v_lshlrev_b32_e32 v206, 16, v30
	v_and_b32_e32 v207, 0xffff0000, v30
	s_cselect_b64 s[24:25], -1, 0
	v_lshlrev_b32_e32 v122, 16, v16
	v_and_b32_e32 v123, 0xffff0000, v16
	v_lshlrev_b32_e32 v198, 16, v17
	v_and_b32_e32 v199, 0xffff0000, v17
	s_and_b64 vcc, exec, s[24:25]
	v_readlane_b32 s45, v251, 1
	v_readlane_b32 s50, v251, 6
	v_readlane_b32 s51, v251, 7
	v_readlane_b32 s52, v251, 8
	v_readlane_b32 s53, v251, 9
	v_readlane_b32 s54, v251, 10
	v_readlane_b32 s55, v251, 11
	v_readlane_b32 s56, v251, 12
	v_readlane_b32 s57, v251, 13
	v_readlane_b32 s58, v251, 14
	v_readlane_b32 s59, v251, 15
	v_pk_fma_f32 v[116:117], v[72:73], v[116:117], v[68:69]
	v_pk_fma_f32 v[192:193], v[74:75], v[192:193], v[70:71]
	v_pk_fma_f32 v[108:109], v[80:81], v[108:109], v[76:77]
	v_pk_fma_f32 v[76:77], v[80:81], v[200:201], v[76:77]
	v_pk_fma_f32 v[184:185], v[82:83], v[184:185], v[78:79]
	v_pk_fma_f32 v[80:81], v[84:85], v[110:111], v[108:109]
	v_pk_fma_f32 v[108:109], v[88:89], v[118:119], v[116:117]
	v_pk_fma_f32 v[76:77], v[84:85], v[202:203], v[76:77]
	v_pk_fma_f32 v[110:111], v[86:87], v[186:187], v[184:185]
	v_pk_fma_f32 v[116:117], v[90:91], v[194:195], v[192:193]
	v_pk_fma_f32 v[80:81], v[92:93], v[112:113], v[80:81]
	v_pk_fma_f32 v[84:85], v[96:97], v[120:121], v[108:109]
	v_pk_fma_f32 v[110:111], v[94:95], v[188:189], v[110:111]
	v_pk_fma_f32 v[108:109], v[100:101], v[114:115], v[80:81]
	v_lshlrev_b32_e32 v80, 16, v20
	v_and_b32_e32 v81, 0xffff0000, v20
	v_pk_fma_f32 v[68:69], v[72:73], v[80:81], v[68:69]
	v_lshlrev_b32_e32 v72, 16, v24
	v_and_b32_e32 v73, 0xffff0000, v24
	v_pk_fma_f32 v[68:69], v[88:89], v[72:73], v[68:69]
	v_lshlrev_b32_e32 v72, 16, v28
	v_and_b32_e32 v73, 0xffff0000, v28
	v_pk_fma_f32 v[68:69], v[96:97], v[72:73], v[68:69]
	v_lshlrev_b32_e32 v72, 16, v32
	v_and_b32_e32 v73, 0xffff0000, v32
	v_pk_fma_f32 v[68:69], v[104:105], v[72:73], v[68:69]
	v_lshlrev_b32_e32 v72, 16, v19
	v_and_b32_e32 v73, 0xffff0000, v19
	v_pk_fma_f32 v[72:73], v[82:83], v[72:73], v[78:79]
	v_lshlrev_b32_e32 v78, 16, v23
	v_and_b32_e32 v79, 0xffff0000, v23
	v_pk_fma_f32 v[72:73], v[86:87], v[78:79], v[72:73]
	v_lshlrev_b32_e32 v78, 16, v27
	v_and_b32_e32 v79, 0xffff0000, v27
	v_pk_fma_f32 v[72:73], v[94:95], v[78:79], v[72:73]
	v_lshlrev_b32_e32 v78, 16, v31
	v_and_b32_e32 v79, 0xffff0000, v31
	v_pk_fma_f32 v[78:79], v[102:103], v[78:79], v[72:73]
	v_lshlrev_b32_e32 v72, 16, v21
	v_and_b32_e32 v73, 0xffff0000, v21
	v_pk_fma_f32 v[70:71], v[74:75], v[72:73], v[70:71]
	v_lshlrev_b32_e32 v72, 16, v25
	v_and_b32_e32 v73, 0xffff0000, v25
	v_pk_fma_f32 v[76:77], v[92:93], v[204:205], v[76:77]
	v_pk_fma_f32 v[70:71], v[90:91], v[72:73], v[70:71]
	v_lshlrev_b32_e32 v72, 16, v29
	v_and_b32_e32 v73, 0xffff0000, v29
	v_pk_fma_f32 v[116:117], v[98:99], v[196:197], v[116:117]
	v_pk_fma_f32 v[110:111], v[102:103], v[190:191], v[110:111]
	v_pk_fma_f32 v[76:77], v[100:101], v[206:207], v[76:77]
	v_pk_fma_f32 v[70:71], v[98:99], v[72:73], v[70:71]
	v_lshlrev_b32_e32 v72, 16, v33
	v_and_b32_e32 v73, 0xffff0000, v33
	v_pk_fma_f32 v[112:113], v[104:105], v[122:123], v[84:85]
	v_pk_fma_f32 v[114:115], v[106:107], v[198:199], v[116:117]
	ds_write_b128 v177, v[108:111]
	ds_write_b128 v177, v[112:115] offset:16
	v_pk_fma_f32 v[70:71], v[106:107], v[72:73], v[70:71]
	ds_write_b128 v177, v[76:79] offset:16896
	ds_write_b128 v177, v[68:71] offset:16912
	s_cbranch_vccnz .LBB0_335
	s_and_b32 s4, s26, 0x780
	v_or_b32_e32 v2, s4, v130
	s_and_b32 s43, s28, 0xfc0
	v_mov_b32_e32 v4, v67
	v_mov_b32_e32 v5, v67
	v_add_u32_e32 v14, s43, v131
	v_lshlrev_b32_e32 v66, 1, v2
	v_mov_b32_e32 v2, v67
	v_mov_b32_e32 v3, v67
	v_mov_b64_e32 v[8:9], v[4:5]
	s_and_b32 s44, s28, 0xfffff000
	v_lshl_add_u64 v[30:31], s[0:1], 0, v[66:67]
	v_cmp_lt_i32_e32 vcc, -1, v14
	v_mov_b64_e32 v[6:7], v[2:3]
	s_and_saveexec_b64 s[4:5], vcc
	s_cbranch_execz .LBB0_328
	v_add_u32_e32 v6, s44, v14
	v_ashrrev_i32_e32 v7, 31, v6
	v_lshlrev_b64 v[6:7], 12, v[6:7]
	v_lshl_add_u64 v[6:7], v[30:31], 0, v[6:7]
	global_load_dwordx4 v[6:9], v[6:7], off

; __device__ __forceinline__ float softplusf_(float x) { return fmaxf(x, 0.f) + log1pf(__expf(-fabsf(x))); }
; template <int PASS> __device__ void lru_phase(const Params& p, unsigned char* smem) {
;     float* xcf = (float*)smem;
;     float* As = xcf + 64 * 132;
;     float* Us = As + 64 * 132;
;     float* qA = Us + 64 * 132;
;     float* qH = qA + 512;
;     const int tid = threadIdx.x, lane = tid & 63, wave = __builtin_amdgcn_readfirstlane(tid >> 6);
;     const u16* XR = (const u16*)(p.ws + OFF_XR);
;     u16* Y0 = (u16*)(p.ws + OFF_Y0);
;     const u16* LW = (const u16*)(p.ws + OFF_LRUW);
;     float* LA = (float*)(p.ws + OFF_LRUA); float* LH = (float*)(p.ws + OFF_LRUH); const float* LC = (const float*)(p.ws + OFF_LRUC);
;     const float* cw = p.in[3]; const float* cb = p.in[4];
;     u32x4 craw[2][4];
;     ...
;     if ((int)blockIdx.x < 4096) LRU_CLOAD((int)blockIdx.x);
;     const bool jb_fixed = (gridDim.x & 15) == 0;
;     bf16x8 hba[4], hbx[4]; float hb_a = 0.f, hb_x = 0.f, hsp = 0.f;
;     if (jb_fixed) { const int jb0 = blockIdx.x & 15, cg0 = jb0 * 128 + 16 * wave + (lane & 15);
; #pragma unroll
;         for (int ks = 0; ks < 4; ++ks) { const size_t wo = (size_t)((jb0 * 128 + 16 * wave + (lane & 15)) * 128 + ks * 32 + 8 * (lane >> 4));
;             hba[ks] = *(const bf16x8*)(LW + wo); hbx[ks] = *(const bf16x8*)(LW + (size_t)16 * 128 * 128 + wo); }
;         hb_a = p.in[6][cg0]; hb_x = p.in[8][cg0]; hsp = softplusf_(-p.in[9][cg0]); }
;     for (int tile = blockIdx.x; tile < 4096; tile += gridDim.x) {
.LBB0_540:
	s_add_u32 s10, s64, 0xc000000
	s_addc_u32 s11, s65, 0
	s_add_u32 s26, s64, 0x1f500000
	v_lshrrev_b32_e32 v70, 2, v1
	s_addc_u32 s27, s65, 0
	v_and_b32_e32 v70, 12, v70
	v_lshrrev_b32_e32 v137, 7, v1
	v_lshrrev_b32_e32 v66, 3, v1
	v_and_b32_e32 v132, 0x7f, v1
	s_add_u32 s14, s64, 0x1f780000
	v_lshl_or_b32 v136, s4, 4, v90
	v_lshlrev_b32_e32 v138, 4, v137
	v_mul_u32_u24_e32 v70, 0x84, v70
	v_and_b32_e32 v131, 0x70, v66
	s_movk_i32 s2, 0x7f
	v_lshlrev_b32_e32 v66, 1, v132
	v_mov_b32_e32 v67, 0
	s_addc_u32 s15, s65, 0
	v_lshlrev_b32_e32 v71, 2, v1
	s_add_i32 s3, 0, 0x18c00
	s_add_i32 s12, 0, 0x10800
	v_add_lshl_u32 v70, v136, v70, 2
	v_or_b32_e32 v159, 1, v138
	v_lshl_add_u64 v[124:125], s[10:11], 0, v[66:67]
	v_lshrrev_b32_e32 v133, 4, v1
	v_lshlrev_b32_e32 v66, 3, v1
	v_lshrrev_b32_e32 v68, 1, v1
	v_add_u32_e32 v139, s3, v71
	s_add_i32 s5, 0, 0x19400
	v_cmp_lt_u32_e64 s[2:3], s2, v1
	v_mul_u32_u24_e32 v1, 0x840, v137
	v_add_u32_e32 v141, 0, v70
	v_add_u32_e32 v142, s12, v70
	v_mul_u32_u24_e32 v70, 0x84, v159
	v_add_u32_e32 v140, s5, v71
	v_add_lshl_u32 v71, v1, v132, 2
	v_add_lshl_u32 v70, v70, v132, 2
	v_add_u32_e32 v1, s12, v71
	v_add_u32_e32 v158, 0, v71
	v_add_u32_e32 v71, 0x210, v70
	v_add_u32_e32 v163, 0, v71
	v_add_u32_e32 v164, s12, v71
	v_add_u32_e32 v71, 0x420, v70
	v_add_u32_e32 v166, 0, v71
	v_add_u32_e32 v167, s12, v71
	v_add_u32_e32 v71, 0x630, v70
	v_add_u32_e32 v169, 0, v71
	v_add_u32_e32 v170, s12, v71
	v_add_u32_e32 v71, 0x840, v70
	v_add_u32_e32 v172, 0, v71
	v_add_u32_e32 v173, s12, v71
	v_add_u32_e32 v71, 0xa50, v70
	v_add_u32_e32 v175, 0, v71
	v_add_u32_e32 v176, s12, v71
	v_add_u32_e32 v71, 0xc60, v70
	v_add_u32_e32 v178, 0, v71
	v_add_u32_e32 v179, s12, v71
	v_add_u32_e32 v71, 0xe70, v70
	v_add_u32_e32 v181, 0, v71
	v_add_u32_e32 v182, s12, v71
	v_add_u32_e32 v71, 0x1080, v70
	v_add_u32_e32 v184, 0, v71
	v_add_u32_e32 v185, s12, v71
	v_add_u32_e32 v71, 0x1290, v70
	v_add_u32_e32 v187, 0, v71
	v_add_u32_e32 v188, s12, v71
	v_add_u32_e32 v71, 0x14a0, v70
	v_add_u32_e32 v190, 0, v71
	v_add_u32_e32 v191, s12, v71
	v_add_u32_e32 v71, 0x16b0, v70
	v_and_b32_e32 v134, 0x78, v66
	v_and_b32_e32 v68, 24, v68
	v_add_u32_e32 v193, 0, v71
	v_add_u32_e32 v194, s12, v71
	v_add_u32_e32 v71, 0x18c0, v70
	v_lshl_add_u32 v66, v134, 2, 0
	v_lshl_add_u32 v69, v68, 2, 0
	v_mul_u32_u24_e32 v72, 0x210, v133
	s_lshl_b32 s4, s4, 11
	v_lshlrev_b32_e32 v73, 7, v90
	v_mul_u32_u24_e32 v74, 0x210, v90
	v_add_u32_e32 v160, 0, v70
	v_add_u32_e32 v161, s12, v70
	v_add_u32_e32 v196, 0, v71
	v_add_u32_e32 v197, s12, v71
	v_add_u32_e32 v71, 0x1ad0, v70
	v_add_u32_e32 v70, 0x1ce0, v70
	s_mov_b32 s13, 0
	v_add_u32_e32 v135, -3, v133
	v_add_u32_e32 v143, 0x210, v142
	v_add_u32_e32 v144, 0x420, v142
	v_add_u32_e32 v145, 0x630, v142
	v_add_u32_e32 v146, 0x2100, v142
	v_add_u32_e32 v147, 0x2310, v142
	v_add_u32_e32 v148, 0x2520, v142
	v_add_u32_e32 v149, 0x2730, v142
	v_add_u32_e32 v150, 0x4200, v142
	v_add_u32_e32 v151, 0x4410, v142
	v_add_u32_e32 v152, 0x4620, v142
	v_add_u32_e32 v153, 0x4830, v142
	v_add_u32_e32 v154, 0x6300, v142
	v_add_u32_e32 v155, 0x6510, v142
	v_add_u32_e32 v156, 0x6720, v142
	v_add_u32_e32 v157, 0x6930, v142
	v_or_b32_e32 v162, 2, v138
	v_or_b32_e32 v165, 3, v138
	v_or_b32_e32 v168, 4, v138
	v_or_b32_e32 v171, 5, v138
	v_or_b32_e32 v174, 6, v138
	v_or_b32_e32 v177, 7, v138
	v_or_b32_e32 v180, 8, v138
	v_or_b32_e32 v183, 9, v138
	v_or_b32_e32 v186, 10, v138
	v_or_b32_e32 v189, 11, v138
	v_or_b32_e32 v192, 12, v138
	v_or_b32_e32 v195, 13, v138
	v_or_b32_e32 v198, 14, v138
	v_add_u32_e32 v199, 0, v71
	v_add_u32_e32 v200, s12, v71
	v_or_b32_e32 v201, 15, v138
	v_add_u32_e32 v202, 0, v70
	v_add_u32_e32 v203, s12, v70
	v_or3_b32 v204, s4, v73, v68
	v_lshl_add_u32 v205, v132, 2, s5
	s_mov_b64 s[16:17], 0x2000
	s_movk_i32 s28, 0x2000
	s_mov_b64 s[18:19], 0x4000
	s_movk_i32 s29, 0x4000
	s_mov_b64 s[20:21], 0x6000
	s_movk_i32 s30, 0x6000
	v_add_u32_e32 v206, v66, v72
	s_mov_b32 s31, 0xbfb8aa3b
	s_mov_b32 s33, 0x3f2aaaab
	v_mov_b32_e32 v207, 0x3ecc95a3
	s_mov_b32 s34, 0x3f317218
	s_mov_b32 s35, 0x7f800000
	s_mov_b32 s36, 0x33800000
	v_add_u32_e32 v208, v69, v74
	v_mov_b32_e32 v126, 0x3f317218
	v_mov_b32_e32 v209, 0x7f800000
	v_mov_b32_e32 v210, 0x7fc00000
	v_mov_b32_e32 v211, 0xff800000
	s_mov_b32 s37, s70
	s_mov_b32 s60, 0
	s_branch .LBB0_542
; __device__ __forceinline__ u16 f2bf(float f) { return (u16)(pk2(f, 0.f) & 0xffffu); }
; __device__ __forceinline__ float bf2f(u16 v) { return __uint_as_float(((unsigned)v) << 16); }
; #define LBAR0() do { asm volatile("s_waitcnt lgkmcnt(0)" ::: "memory"); __builtin_amdgcn_s_barrier(); asm volatile("" ::: "memory"); } while (0)
; __device__ __forceinline__ float fsig0(float x) { return __builtin_amdgcn_rcpf(1.0f + __expf(-x)); }
; template <int PASS> __device__ void lru_phase(const Params& p, unsigned char* smem) {
;     ...
;             float carry = LC[(size_t)(b * 64 + c) * 2048 + cgl];
;             for (int qq = 0; qq < q; ++qq) carry = qA[qq * 128 + ch] * carry + qH[qq * 128 + ch];
; #pragma unroll
;             for (int tt = 0; tt < 16; ++tt) { const int t = q * 16 + tt; const float hh = Us[t * 132 + ch] + As[t * 132 + ch] * carry; const float z = bf2f(zpre[tt]);
;                 Y0[(size_t)(row0 + t) * 4096 + cgl] = f2bf(hh * z * fsig0(z)); }
;         }
;         LBAR0();
.LBB0_541:
	s_or_b64 exec, exec, s[4:5]
	s_waitcnt vmcnt(0)
	v_lshlrev_b32_e32 v71, 16, v227
	v_mul_f32_e32 v68, 0xbfb8aa3b, v71
	v_exp_f32_e32 v68, v68
	ds_read_b32 v72, v1
	ds_read_b32 v73, v158 offset:33792
	v_lshlrev_b32_e32 v66, 1, v66
	s_and_b64 vcc, exec, s[22:23]
	v_add_f32_e32 v68, 1.0, v68
	v_rcp_f32_e32 v74, v68
	s_waitcnt vmcnt(0) lgkmcnt(0)
	v_fmac_f32_e32 v72, v70, v73
	v_lshl_add_u64 v[68:69], s[10:11], 0, v[66:67]
	v_mul_f32_e32 v66, v72, v71
	v_lshlrev_b32_e32 v71, 16, v226
	v_mul_f32_e32 v66, v74, v66
	v_mul_f32_e32 v74, 0xbfb8aa3b, v71
	v_exp_f32_e32 v74, v74
	v_cvt_pk_bf16_f32 v66, v66, v67
	ds_read_b32 v75, v161
	ds_read_b32 v76, v160 offset:33792
	v_add_u32_e32 v72, s38, v138
	v_add_f32_e32 v74, 1.0, v74
	v_ashrrev_i32_e32 v73, 31, v72
	v_rcp_f32_e32 v74, v74
	v_lshlrev_b64 v[72:73], 13, v[72:73]
	v_lshl_add_u64 v[72:73], v[68:69], 0, v[72:73]
	s_waitcnt lgkmcnt(0)
	v_fmac_f32_e32 v75, v70, v76
	global_store_short v[72:73], v66, off
	v_mul_f32_e32 v66, v75, v71
	v_lshlrev_b32_e32 v71, 16, v225
	v_mul_f32_e32 v66, v74, v66
	v_mul_f32_e32 v74, 0xbfb8aa3b, v71
	v_exp_f32_e32 v74, v74
	v_cvt_pk_bf16_f32 v66, v66, v67
	ds_read_b32 v75, v164
	ds_read_b32 v76, v163 offset:33792
	v_add_u32_e32 v72, s38, v159
	v_add_f32_e32 v74, 1.0, v74
	v_ashrrev_i32_e32 v73, 31, v72
	v_rcp_f32_e32 v74, v74
	v_lshlrev_b64 v[72:73], 13, v[72:73]
	v_lshl_add_u64 v[72:73], v[68:69], 0, v[72:73]
	s_waitcnt lgkmcnt(0)
	v_fmac_f32_e32 v75, v70, v76
	global_store_short v[72:73], v66, off
	v_mul_f32_e32 v66, v75, v71
	v_lshlrev_b32_e32 v71, 16, v224
	v_mul_f32_e32 v66, v74, v66
	v_mul_f32_e32 v74, 0xbfb8aa3b, v71
	v_exp_f32_e32 v74, v74
	v_cvt_pk_bf16_f32 v66, v66, v67
	ds_read_b32 v75, v167
	ds_read_b32 v76, v166 offset:33792
	v_add_u32_e32 v72, s38, v162
	v_add_f32_e32 v74, 1.0, v74
	v_ashrrev_i32_e32 v73, 31, v72
	v_rcp_f32_e32 v74, v74
	v_lshlrev_b64 v[72:73], 13, v[72:73]
	v_lshl_add_u64 v[72:73], v[68:69], 0, v[72:73]
	s_waitcnt lgkmcnt(0)
	v_fmac_f32_e32 v75, v70, v76
	global_store_short v[72:73], v66, off
	v_mul_f32_e32 v66, v75, v71
	v_lshlrev_b32_e32 v71, 16, v223
	v_mul_f32_e32 v66, v74, v66
	v_mul_f32_e32 v74, 0xbfb8aa3b, v71
	v_exp_f32_e32 v74, v74
	v_cvt_pk_bf16_f32 v66, v66, v67
	ds_read_b32 v75, v170
	ds_read_b32 v76, v169 offset:33792
	v_add_u32_e32 v72, s38, v165
	v_add_f32_e32 v74, 1.0, v74
	v_ashrrev_i32_e32 v73, 31, v72
	v_rcp_f32_e32 v74, v74
	v_lshlrev_b64 v[72:73], 13, v[72:73]
	v_lshl_add_u64 v[72:73], v[68:69], 0, v[72:73]
	s_waitcnt lgkmcnt(0)
	v_fmac_f32_e32 v75, v70, v76
	global_store_short v[72:73], v66, off
	v_mul_f32_e32 v66, v75, v71
	v_lshlrev_b32_e32 v71, 16, v222
	v_mul_f32_e32 v66, v74, v66
	v_mul_f32_e32 v74, 0xbfb8aa3b, v71
	v_exp_f32_e32 v74, v74
	v_cvt_pk_bf16_f32 v66, v66, v67
	ds_read_b32 v75, v173
	ds_read_b32 v76, v172 offset:33792
	v_add_u32_e32 v72, s38, v168
	v_add_f32_e32 v74, 1.0, v74
	v_ashrrev_i32_e32 v73, 31, v72
	v_rcp_f32_e32 v74, v74
	v_lshlrev_b64 v[72:73], 13, v[72:73]
	v_lshl_add_u64 v[72:73], v[68:69], 0, v[72:73]
	s_waitcnt lgkmcnt(0)
	v_fmac_f32_e32 v75, v70, v76
	global_store_short v[72:73], v66, off
	v_mul_f32_e32 v66, v75, v71
	v_lshlrev_b32_e32 v71, 16, v221
	v_mul_f32_e32 v66, v74, v66
	v_mul_f32_e32 v74, 0xbfb8aa3b, v71
	v_exp_f32_e32 v74, v74
	v_cvt_pk_bf16_f32 v66, v66, v67
	ds_read_b32 v75, v176
	ds_read_b32 v76, v175 offset:33792
	v_add_u32_e32 v72, s38, v171
	v_add_f32_e32 v74, 1.0, v74
	v_ashrrev_i32_e32 v73, 31, v72
	v_rcp_f32_e32 v74, v74
	v_lshlrev_b64 v[72:73], 13, v[72:73]
	v_lshl_add_u64 v[72:73], v[68:69], 0, v[72:73]
	s_waitcnt lgkmcnt(0)
	v_fmac_f32_e32 v75, v70, v76
	global_store_short v[72:73], v66, off
	v_mul_f32_e32 v66, v75, v71
	v_lshlrev_b32_e32 v71, 16, v219
	v_mul_f32_e32 v66, v74, v66
	v_mul_f32_e32 v74, 0xbfb8aa3b, v71
	v_exp_f32_e32 v74, v74
	v_cvt_pk_bf16_f32 v66, v66, v67
	ds_read_b32 v75, v179
	ds_read_b32 v76, v178 offset:33792
	v_add_u32_e32 v72, s38, v174
	v_add_f32_e32 v74, 1.0, v74
	v_ashrrev_i32_e32 v73, 31, v72
	v_rcp_f32_e32 v74, v74
	v_lshlrev_b64 v[72:73], 13, v[72:73]
	v_lshl_add_u64 v[72:73], v[68:69], 0, v[72:73]
	s_waitcnt lgkmcnt(0)
	v_fmac_f32_e32 v75, v70, v76
	global_store_short v[72:73], v66, off
	v_mul_f32_e32 v66, v75, v71
	v_lshlrev_b32_e32 v71, 16, v220
	v_mul_f32_e32 v66, v74, v66
	v_mul_f32_e32 v74, 0xbfb8aa3b, v71
	v_exp_f32_e32 v74, v74
	v_cvt_pk_bf16_f32 v66, v66, v67
	ds_read_b32 v75, v182
	ds_read_b32 v76, v181 offset:33792
	v_add_u32_e32 v72, s38, v177
	v_add_f32_e32 v74, 1.0, v74
	v_ashrrev_i32_e32 v73, 31, v72
	v_rcp_f32_e32 v74, v74
	v_lshlrev_b64 v[72:73], 13, v[72:73]
	v_lshl_add_u64 v[72:73], v[68:69], 0, v[72:73]
	s_waitcnt lgkmcnt(0)
	v_fmac_f32_e32 v75, v70, v76
	global_store_short v[72:73], v66, off
	v_mul_f32_e32 v66, v75, v71
	v_lshlrev_b32_e32 v71, 16, v218
	v_mul_f32_e32 v66, v74, v66
	v_mul_f32_e32 v74, 0xbfb8aa3b, v71
	v_exp_f32_e32 v74, v74
	v_cvt_pk_bf16_f32 v66, v66, v67
	ds_read_b32 v75, v185
	ds_read_b32 v76, v184 offset:33792
	v_add_u32_e32 v72, s38, v180
	v_add_f32_e32 v74, 1.0, v74
	v_ashrrev_i32_e32 v73, 31, v72
	v_rcp_f32_e32 v74, v74
	v_lshlrev_b64 v[72:73], 13, v[72:73]
	v_lshl_add_u64 v[72:73], v[68:69], 0, v[72:73]
	s_waitcnt lgkmcnt(0)
	v_fmac_f32_e32 v75, v70, v76
	global_store_short v[72:73], v66, off
	v_mul_f32_e32 v66, v75, v71
	v_lshlrev_b32_e32 v71, 16, v217
	v_mul_f32_e32 v66, v74, v66
	v_mul_f32_e32 v74, 0xbfb8aa3b, v71
	v_exp_f32_e32 v74, v74
	v_cvt_pk_bf16_f32 v66, v66, v67
	ds_read_b32 v75, v188
	ds_read_b32 v76, v187 offset:33792
	v_add_u32_e32 v72, s38, v183
	v_add_f32_e32 v74, 1.0, v74
	v_ashrrev_i32_e32 v73, 31, v72
	v_rcp_f32_e32 v74, v74
	v_lshlrev_b64 v[72:73], 13, v[72:73]
	v_lshl_add_u64 v[72:73], v[68:69], 0, v[72:73]
	s_waitcnt lgkmcnt(0)
; __device__ __forceinline__ u16 f2bf(float f) { return (u16)(pk2(f, 0.f) & 0xffffu); }
; __device__ __forceinline__ float bf2f(u16 v) { return __uint_as_float(((unsigned)v) << 16); }
; __device__ __forceinline__ void unpack8(u32x4 w, float* f) { f[0] = bflo(w.x); f[1] = bfhi(w.x); f[2] = bflo(w.y); f[3] = bfhi(w.y); f[4] = bflo(w.z); f[5] = bfhi(w.z); f[6] = bflo(w.w); f[7] = bfhi(w.w); }
; #define LBAR0() do { asm volatile("s_waitcnt lgkmcnt(0)" ::: "memory"); __builtin_amdgcn_s_barrier(); asm volatile("" ::: "memory"); } while (0)
; __device__ __forceinline__ float fsig0(float x) { return __builtin_amdgcn_rcpf(1.0f + __expf(-x)); }
; template <int PASS> __device__ void lru_phase(const Params& p, unsigned char* smem) {
;     ...
;             { const f32x4 b0 = *(const f32x4*)(cb + ch), b1 = *(const f32x4*)(cb + ch + 4);
; #pragma unroll
;               for (int i = 0; i < 4; ++i) { acc[i] = b0[i]; acc[4 + i] = b1[i]; } }
; #pragma unroll
;             for (int j = 0; j < 4; ++j) { float xv[8]; unpack8(craw[it][j], xv);
;                 const f32x4 w0 = *(const f32x4*)(cw + j * 2048 + ch), w1 = *(const f32x4*)(cw + j * 2048 + ch + 4);
;     ...
;             float carry = LC[(size_t)(b * 64 + c) * 2048 + cgl];
;             for (int qq = 0; qq < q; ++qq) carry = qA[qq * 128 + ch] * carry + qH[qq * 128 + ch];
; #pragma unroll
;             for (int tt = 0; tt < 16; ++tt) { const int t = q * 16 + tt; const float hh = Us[t * 132 + ch] + As[t * 132 + ch] * carry; const float z = bf2f(zpre[tt]);
;                 Y0[(size_t)(row0 + t) * 4096 + cgl] = f2bf(hh * z * fsig0(z)); }
;         }
;         LBAR0();
	v_fmac_f32_e32 v75, v70, v76
	global_store_short v[72:73], v66, off
	v_mul_f32_e32 v66, v75, v71
	v_lshlrev_b32_e32 v71, 16, v216
	v_mul_f32_e32 v66, v74, v66
	v_mul_f32_e32 v74, 0xbfb8aa3b, v71
	v_exp_f32_e32 v74, v74
	v_cvt_pk_bf16_f32 v66, v66, v67
	ds_read_b32 v75, v191
	ds_read_b32 v76, v190 offset:33792
	v_add_u32_e32 v72, s38, v186
	v_add_f32_e32 v74, 1.0, v74
	v_ashrrev_i32_e32 v73, 31, v72
	v_rcp_f32_e32 v74, v74
	v_lshlrev_b64 v[72:73], 13, v[72:73]
	v_lshl_add_u64 v[72:73], v[68:69], 0, v[72:73]
	s_waitcnt lgkmcnt(0)
	v_fmac_f32_e32 v75, v70, v76
	global_store_short v[72:73], v66, off
	v_mul_f32_e32 v66, v75, v71
	v_lshlrev_b32_e32 v71, 16, v215
	v_mul_f32_e32 v66, v74, v66
	v_mul_f32_e32 v74, 0xbfb8aa3b, v71
	v_exp_f32_e32 v74, v74
	v_cvt_pk_bf16_f32 v66, v66, v67
	ds_read_b32 v75, v194
	ds_read_b32 v76, v193 offset:33792
	v_add_u32_e32 v72, s38, v189
	v_add_f32_e32 v74, 1.0, v74
	v_ashrrev_i32_e32 v73, 31, v72
	v_rcp_f32_e32 v74, v74
	v_lshlrev_b64 v[72:73], 13, v[72:73]
	v_lshl_add_u64 v[72:73], v[68:69], 0, v[72:73]
	s_waitcnt lgkmcnt(0)
	v_fmac_f32_e32 v75, v70, v76
	global_store_short v[72:73], v66, off
	v_mul_f32_e32 v66, v75, v71
	v_lshlrev_b32_e32 v71, 16, v214
	v_mul_f32_e32 v66, v74, v66
	v_mul_f32_e32 v74, 0xbfb8aa3b, v71
	v_exp_f32_e32 v74, v74
	v_cvt_pk_bf16_f32 v66, v66, v67
	ds_read_b32 v75, v197
	ds_read_b32 v76, v196 offset:33792
	v_add_u32_e32 v72, s38, v192
	v_add_f32_e32 v74, 1.0, v74
	v_ashrrev_i32_e32 v73, 31, v72
	v_rcp_f32_e32 v74, v74
	v_lshlrev_b64 v[72:73], 13, v[72:73]
	v_lshl_add_u64 v[72:73], v[68:69], 0, v[72:73]
	s_waitcnt lgkmcnt(0)
	v_fmac_f32_e32 v75, v70, v76
	global_store_short v[72:73], v66, off
	v_mul_f32_e32 v66, v75, v71
	v_lshlrev_b32_e32 v71, 16, v213
	v_mul_f32_e32 v66, v74, v66
	v_mul_f32_e32 v74, 0xbfb8aa3b, v71
	v_exp_f32_e32 v74, v74
	v_cvt_pk_bf16_f32 v66, v66, v67
	ds_read_b32 v75, v200
	ds_read_b32 v76, v199 offset:33792
	v_add_u32_e32 v72, s38, v195
	v_add_f32_e32 v74, 1.0, v74
	v_ashrrev_i32_e32 v73, 31, v72
	v_rcp_f32_e32 v74, v74
	v_lshlrev_b64 v[72:73], 13, v[72:73]
	v_lshl_add_u64 v[72:73], v[68:69], 0, v[72:73]
	s_waitcnt lgkmcnt(0)
	v_fmac_f32_e32 v75, v70, v76
	global_store_short v[72:73], v66, off
	v_mul_f32_e32 v66, v75, v71
	v_lshlrev_b32_e32 v71, 16, v212
	v_mul_f32_e32 v66, v74, v66
	v_mul_f32_e32 v74, 0xbfb8aa3b, v71
	v_exp_f32_e32 v74, v74
	v_cvt_pk_bf16_f32 v66, v66, v67
	ds_read_b32 v75, v203
	ds_read_b32 v76, v202 offset:33792
	v_add_u32_e32 v72, s38, v198
	v_ashrrev_i32_e32 v73, 31, v72
	v_add_f32_e32 v74, 1.0, v74
	v_lshlrev_b64 v[72:73], 13, v[72:73]
	v_rcp_f32_e32 v74, v74
	v_lshl_add_u64 v[72:73], v[68:69], 0, v[72:73]
	s_waitcnt lgkmcnt(0)
	v_fmac_f32_e32 v75, v70, v76
	v_add_u32_e32 v70, s38, v201
	global_store_short v[72:73], v66, off
	v_mul_f32_e32 v66, v75, v71
	v_ashrrev_i32_e32 v71, 31, v70
	v_lshlrev_b64 v[70:71], 13, v[70:71]
	v_mul_f32_e32 v66, v74, v66
	v_lshl_add_u64 v[68:69], v[68:69], 0, v[70:71]
	v_cvt_pk_bf16_f32 v66, v66, v67
	global_store_short v[68:69], v66, off
	s_waitcnt lgkmcnt(0)
	s_barrier
	s_cbranch_vccnz .LBB0_578
.LBB0_542:
	s_cmp_eq_u32 s60, 0
	s_cselect_b64 vcc, -1, s[8:9]
	s_mov_b32 s60, 1
	s_cbranch_vccz LRUW2_staged
	v_readlane_b32 s76, v251, 2
	v_readlane_b32 s77, v251, 3
	v_readlane_b32 s78, v251, 4
	v_readlane_b32 s79, v251, 5
	s_and_b32 s61, s37, 15
	s_lshl_b32 s61, s61, 9
	v_and_b32_e32 v248, 0x3ff, v0
	v_and_b32_e32 v249, 15, v248
	v_lshlrev_b32_e32 v249, 5, v249
	v_add_u32_e32 v249, 0x1a000, v249
	v_cmp_gt_u32_e32 vcc, 0xa0, v248
	s_and_saveexec_b64 s[82:83], vcc
	s_cbranch_execz LRUW2_nost
	v_lshrrev_b32_e32 v247, 5, v248
	v_and_b32_e32 v246, 31, v248
	v_lshlrev_b32_e32 v246, 4, v246
	v_add_u32_e32 v246, s61, v246
	v_cmp_eq_u32_e32 vcc, 4, v247
	v_lshlrev_b32_e32 v247, 13, v247
	v_add_u32_e32 v247, v247, v246
	v_cndmask_b32_e32 v247, v247, v246, vcc
	v_mov_b32_e32 v244, s76
	v_mov_b32_e32 v245, s77
	v_mov_b32_e32 v242, s78
	v_mov_b32_e32 v243, s79
	v_cndmask_b32_e32 v244, v244, v242, vcc
	v_cndmask_b32_e32 v245, v245, v243, vcc
	v_add_co_u32_e32 v244, vcc, v244, v247
	s_nop 1
	v_addc_co_u32_e32 v245, vcc, 0, v245, vcc
	global_load_dwordx4 v[236:239], v[244:245], off
	v_lshlrev_b32_e32 v246, 4, v248
	v_add_u32_e32 v246, 0x1a000, v246
	s_waitcnt vmcnt(0)
	ds_write_b128 v246, v[236:239]
LRUW2_nost:
	s_or_b64 exec, exec, s[82:83]
	s_waitcnt lgkmcnt(0)
	s_barrier
; __device__ __forceinline__ void unpack8(u32x4 w, float* f) { f[0] = bflo(w.x); f[1] = bfhi(w.x); f[2] = bflo(w.y); f[3] = bfhi(w.y); f[4] = bflo(w.z); f[5] = bfhi(w.z); f[6] = bflo(w.w); f[7] = bfhi(w.w); }
; template <int PASS> __device__ void lru_phase(const Params& p, unsigned char* smem) {
;     ...
;         const int jb = tile & 15, c = (tile >> 4) & 63, b = tile >> 10;
;         const int row0 = b * SEQL + c * 64;
;         u16 zpre[16];
;         if (PASS == 2) {
; #pragma unroll
;             for (int tt = 0; tt < 16; ++tt) zpre[tt] = Y0[(size_t)(row0 + (tid >> 7) * 16 + tt) * 4096 + jb * 128 + (tid & 127)];
;         }
; #pragma unroll
;         for (int it = 0; it < 2; ++it) {
;             const int t = (tid >> 4) + 32 * it, c8 = (tid & 15) * 8, ch = jb * 128 + c8;
;             float acc[8];
;             { const f32x4 b0 = *(const f32x4*)(cb + ch), b1 = *(const f32x4*)(cb + ch + 4);
; #pragma unroll
;               for (int i = 0; i < 4; ++i) { acc[i] = b0[i]; acc[4 + i] = b1[i]; } }
; #pragma unroll
;             for (int j = 0; j < 4; ++j) { float xv[8]; unpack8(craw[it][j], xv);
;                 const f32x4 w0 = *(const f32x4*)(cw + j * 2048 + ch), w1 = *(const f32x4*)(cw + j * 2048 + ch + 4);
LRUW2_staged:
	s_bfe_u32 s24, s37, 0x60004
	s_ashr_i32 s25, s37, 10
	s_lshl_b32 s4, s25, 12
	s_lshl_b32 s5, s24, 6
	s_or_b32 s38, s5, s4
	s_and_b32 s40, s37, 15
	v_add_u32_e32 v108, s38, v131
	s_lshl_b32 s12, s40, 8
	v_ashrrev_i32_e32 v109, 31, v108
	v_lshl_add_u64 v[110:111], v[124:125], 0, s[12:13]
	v_lshlrev_b64 v[68:69], 13, v[108:109]
	v_lshl_add_u64 v[112:113], v[110:111], 0, v[68:69]
	v_or_b32_e32 v68, 1, v108
	v_ashrrev_i32_e32 v69, 31, v68
	v_lshlrev_b64 v[68:69], 13, v[68:69]
	v_lshl_add_u64 v[114:115], v[110:111], 0, v[68:69]
	v_or_b32_e32 v68, 2, v108
	v_ashrrev_i32_e32 v69, 31, v68
	s_lshl_b32 s39, s40, 7
	v_lshlrev_b64 v[68:69], 13, v[68:69]
	v_readlane_b32 s44, v251, 0
	v_lshl_add_u64 v[116:117], v[110:111], 0, v[68:69]
	v_or_b32_e32 v68, 3, v108
	v_or_b32_e32 v66, s39, v134
	v_readlane_b32 s46, v251, 2
	v_readlane_b32 s47, v251, 3
	v_ashrrev_i32_e32 v69, 31, v68
	v_lshlrev_b32_e32 v66, 2, v66
	s_mov_b64 s[42:43], s[46:47]
	v_lshlrev_b64 v[68:69], 13, v[68:69]
	v_lshl_add_u64 v[104:105], s[42:43], 0, v[66:67]
	v_lshl_add_u64 v[118:119], v[110:111], 0, v[68:69]
	v_or_b32_e32 v68, 4, v108
	v_add_co_u32_e32 v76, vcc, s28, v104
	v_ashrrev_i32_e32 v69, 31, v68
	s_nop 0
	v_addc_co_u32_e32 v77, vcc, 0, v105, vcc
	v_lshlrev_b64 v[68:69], 13, v[68:69]
	v_readlane_b32 s48, v251, 4
	v_readlane_b32 s49, v251, 5
	v_add_co_u32_e32 v80, vcc, s29, v104
	v_lshl_add_u64 v[120:121], v[110:111], 0, v[68:69]
	s_nop 2
	ds_read_b128 v[68:71], v249 offset:2048
	ds_read_b128 v[72:75], v249
	v_addc_co_u32_e32 v81, vcc, 0, v105, vcc
	ds_read_b128 v[76:79], v249 offset:512
	v_add_co_u32_e32 v84, vcc, s30, v104
	ds_read_b128 v[80:83], v249 offset:1024
	s_nop 0
	v_addc_co_u32_e32 v85, vcc, 0, v105, vcc
	ds_read_b128 v[84:87], v249 offset:1536
	v_or_b32_e32 v100, 5, v108
	ds_read_b128 v[88:91], v249 offset:2064
	ds_read_b128 v[92:95], v249 offset:16
	v_ashrrev_i32_e32 v101, 31, v100
	v_lshl_add_u64 v[96:97], v[104:105], 0, s[16:17]
	ds_read_b128 v[96:99], v249 offset:528
	v_lshlrev_b64 v[106:107], 13, v[100:101]
	v_lshl_add_u64 v[100:101], v[104:105], 0, s[18:19]
	ds_read_b128 v[100:103], v249 offset:1040
	v_lshl_add_u64 v[104:105], v[104:105], 0, s[20:21]
	v_lshl_add_u64 v[122:123], v[110:111], 0, v[106:107]
	ds_read_b128 v[104:107], v249 offset:1552
	v_or_b32_e32 v212, 6, v108
	v_ashrrev_i32_e32 v213, 31, v212
	v_or_b32_e32 v214, 7, v108
	v_lshlrev_b64 v[212:213], 13, v[212:213]
	v_ashrrev_i32_e32 v215, 31, v214
	v_lshl_add_u64 v[212:213], v[110:111], 0, v[212:213]
	v_lshlrev_b64 v[214:215], 13, v[214:215]
	v_lshl_add_u64 v[214:215], v[110:111], 0, v[214:215]
	global_load_ushort v227, v[112:113], off
	global_load_ushort v226, v[114:115], off
	global_load_ushort v225, v[116:117], off
	global_load_ushort v224, v[118:119], off
	global_load_ushort v223, v[120:121], off
	global_load_ushort v222, v[122:123], off
	global_load_ushort v221, v[212:213], off
	global_load_ushort v219, v[214:215], off
	v_or_b32_e32 v112, 8, v108
	v_or_b32_e32 v212, 14, v108
	v_ashrrev_i32_e32 v113, 31, v112
	v_or_b32_e32 v114, 9, v108
	v_or_b32_e32 v116, 10, v108
	v_or_b32_e32 v118, 11, v108
	v_or_b32_e32 v120, 12, v108
	v_or_b32_e32 v122, 13, v108
	v_ashrrev_i32_e32 v213, 31, v212
	v_or_b32_e32 v108, 15, v108
	v_lshlrev_b64 v[112:113], 13, v[112:113]
	v_ashrrev_i32_e32 v115, 31, v114
	v_ashrrev_i32_e32 v117, 31, v116
	v_ashrrev_i32_e32 v119, 31, v118
	v_ashrrev_i32_e32 v121, 31, v120
	v_ashrrev_i32_e32 v123, 31, v122
	v_lshlrev_b64 v[212:213], 13, v[212:213]
	v_ashrrev_i32_e32 v109, 31, v108
	v_lshl_add_u64 v[112:113], v[110:111], 0, v[112:113]
	v_lshlrev_b64 v[114:115], 13, v[114:115]
	v_lshlrev_b64 v[116:117], 13, v[116:117]
	v_lshlrev_b64 v[118:119], 13, v[118:119]
	v_lshlrev_b64 v[120:121], 13, v[120:121]
	v_lshlrev_b64 v[122:123], 13, v[122:123]
	v_lshl_add_u64 v[212:213], v[110:111], 0, v[212:213]
	v_lshlrev_b64 v[108:109], 13, v[108:109]
	v_lshl_add_u64 v[114:115], v[110:111], 0, v[114:115]
	v_lshl_add_u64 v[116:117], v[110:111], 0, v[116:117]
	v_lshl_add_u64 v[118:119], v[110:111], 0, v[118:119]
	v_lshl_add_u64 v[120:121], v[110:111], 0, v[120:121]
	v_lshl_add_u64 v[122:123], v[110:111], 0, v[122:123]
	v_lshl_add_u64 v[108:109], v[110:111], 0, v[108:109]
	global_load_ushort v220, v[112:113], off
	global_load_ushort v218, v[114:115], off
	global_load_ushort v217, v[116:117], off
	global_load_ushort v216, v[118:119], off
	global_load_ushort v215, v[120:121], off
	global_load_ushort v214, v[122:123], off
	s_nop 0
	global_load_ushort v213, v[212:213], off
	s_nop 0
	global_load_ushort v212, v[108:109], off
	s_waitcnt vmcnt(16) lgkmcnt(0)
; __device__ __forceinline__ void unpack8(u32x4 w, float* f) { f[0] = bflo(w.x); f[1] = bfhi(w.x); f[2] = bflo(w.y); f[3] = bfhi(w.y); f[4] = bflo(w.z); f[5] = bfhi(w.z); f[6] = bflo(w.w); f[7] = bfhi(w.w); }
; template <int PASS> __device__ void lru_phase(const Params& p, unsigned char* smem) {
;     ...
;         for (int it = 0; it < 2; ++it) {
;             const int t = (tid >> 4) + 32 * it, c8 = (tid & 15) * 8, ch = jb * 128 + c8;
;             float acc[8];
;             { const f32x4 b0 = *(const f32x4*)(cb + ch), b1 = *(const f32x4*)(cb + ch + 4);
; #pragma unroll
;               for (int i = 0; i < 4; ++i) { acc[i] = b0[i]; acc[4 + i] = b1[i]; } }
; #pragma unroll
;             for (int j = 0; j < 4; ++j) { float xv[8]; unpack8(craw[it][j], xv);
;                 const f32x4 w0 = *(const f32x4*)(cw + j * 2048 + ch), w1 = *(const f32x4*)(cw + j * 2048 + ch + 4);
; #pragma unroll
;                 for (int i = 0; i < 4; ++i) { acc[i] += w0[i] * xv[i]; acc[4 + i] += w1[i] * xv[4 + i]; } }
;             *(f32x4*)(xcf + t * 132 + c8) = (f32x4){acc[0], acc[1], acc[2], acc[3]}; *(f32x4*)(xcf + t * 132 + c8 + 4) = (f32x4){acc[4], acc[5], acc[6], acc[7]};
;         }
;         if (tile + (int)gridDim.x < 4096) LRU_CLOAD(tile + (int)gridDim.x);
	v_lshlrev_b32_e32 v108, 16, v6
	v_and_b32_e32 v109, 0xffff0000, v6
	v_lshlrev_b32_e32 v110, 16, v2
	v_and_b32_e32 v111, 0xffff0000, v2
	v_lshlrev_b32_e32 v112, 16, v4
	v_and_b32_e32 v113, 0xffff0000, v4
	v_lshlrev_b32_e32 v114, 16, v3
	v_and_b32_e32 v115, 0xffff0000, v3
	v_lshlrev_b32_e32 v116, 16, v5
	v_and_b32_e32 v117, 0xffff0000, v5
	s_add_i32 s37, s37, s62
	s_cmpk_gt_i32 s37, 0xfff
	s_cselect_b64 s[22:23], -1, 0
	s_and_b64 vcc, exec, s[22:23]
	v_readlane_b32 s45, v251, 1
	v_readlane_b32 s50, v251, 6
	v_readlane_b32 s51, v251, 7
	v_pk_fma_f32 v[108:109], v[72:73], v[108:109], v[68:69]
	v_readlane_b32 s52, v251, 8
	v_readlane_b32 s53, v251, 9
	v_pk_fma_f32 v[108:109], v[76:77], v[110:111], v[108:109]
	v_lshlrev_b32_e32 v110, 16, v10
	v_and_b32_e32 v111, 0xffff0000, v10
	v_pk_fma_f32 v[108:109], v[80:81], v[110:111], v[108:109]
	v_lshlrev_b32_e32 v110, 16, v14
	v_and_b32_e32 v111, 0xffff0000, v14
	v_pk_fma_f32 v[108:109], v[84:85], v[110:111], v[108:109]
	v_lshlrev_b32_e32 v110, 16, v8
	v_and_b32_e32 v111, 0xffff0000, v8
	v_pk_fma_f32 v[110:111], v[92:93], v[110:111], v[88:89]
	v_readlane_b32 s54, v251, 10
	v_pk_fma_f32 v[110:111], v[96:97], v[112:113], v[110:111]
	v_lshlrev_b32_e32 v112, 16, v12
	v_and_b32_e32 v113, 0xffff0000, v12
	v_pk_fma_f32 v[110:111], v[100:101], v[112:113], v[110:111]
	v_lshlrev_b32_e32 v112, 16, v16
	v_and_b32_e32 v113, 0xffff0000, v16
	v_pk_fma_f32 v[112:113], v[104:105], v[112:113], v[110:111]
	v_lshlrev_b32_e32 v110, 16, v7
	v_and_b32_e32 v111, 0xffff0000, v7
	v_pk_fma_f32 v[110:111], v[74:75], v[110:111], v[70:71]
	v_readlane_b32 s55, v251, 11
	v_pk_fma_f32 v[110:111], v[78:79], v[114:115], v[110:111]
	v_lshlrev_b32_e32 v114, 16, v11
	v_and_b32_e32 v115, 0xffff0000, v11
	v_pk_fma_f32 v[110:111], v[82:83], v[114:115], v[110:111]
	v_lshlrev_b32_e32 v114, 16, v15
	v_and_b32_e32 v115, 0xffff0000, v15
	v_pk_fma_f32 v[110:111], v[86:87], v[114:115], v[110:111]
	v_lshlrev_b32_e32 v114, 16, v9
	v_and_b32_e32 v115, 0xffff0000, v9
	v_pk_fma_f32 v[114:115], v[94:95], v[114:115], v[90:91]
	v_readlane_b32 s56, v251, 12
	v_pk_fma_f32 v[114:115], v[98:99], v[116:117], v[114:115]
	v_lshlrev_b32_e32 v116, 16, v13
	v_and_b32_e32 v117, 0xffff0000, v13
	v_pk_fma_f32 v[114:115], v[102:103], v[116:117], v[114:115]
	v_lshlrev_b32_e32 v116, 16, v17
	v_and_b32_e32 v117, 0xffff0000, v17
	v_pk_fma_f32 v[114:115], v[106:107], v[116:117], v[114:115]
	ds_write_b128 v206, v[108:111]
	ds_write_b128 v206, v[112:115] offset:16
	v_lshlrev_b32_e32 v108, 16, v18
	v_and_b32_e32 v109, 0xffff0000, v18
	v_pk_fma_f32 v[68:69], v[72:73], v[108:109], v[68:69]
	v_lshlrev_b32_e32 v72, 16, v22
	v_and_b32_e32 v73, 0xffff0000, v22
	v_pk_fma_f32 v[68:69], v[76:77], v[72:73], v[68:69]
	v_lshlrev_b32_e32 v72, 16, v26
	v_and_b32_e32 v73, 0xffff0000, v26
	v_pk_fma_f32 v[68:69], v[80:81], v[72:73], v[68:69]
	v_lshlrev_b32_e32 v72, 16, v30
	v_and_b32_e32 v73, 0xffff0000, v30
	v_pk_fma_f32 v[68:69], v[84:85], v[72:73], v[68:69]
	v_lshlrev_b32_e32 v72, 16, v20
	v_and_b32_e32 v73, 0xffff0000, v20
	v_pk_fma_f32 v[72:73], v[92:93], v[72:73], v[88:89]
	v_lshlrev_b32_e32 v76, 16, v24
	v_and_b32_e32 v77, 0xffff0000, v24
	v_pk_fma_f32 v[72:73], v[96:97], v[76:77], v[72:73]
	v_lshlrev_b32_e32 v76, 16, v28
	v_and_b32_e32 v77, 0xffff0000, v28
	v_pk_fma_f32 v[72:73], v[100:101], v[76:77], v[72:73]
	v_lshlrev_b32_e32 v76, 16, v32
	v_and_b32_e32 v77, 0xffff0000, v32
	v_pk_fma_f32 v[72:73], v[104:105], v[76:77], v[72:73]
	v_lshlrev_b32_e32 v76, 16, v19
	v_and_b32_e32 v77, 0xffff0000, v19
	v_pk_fma_f32 v[70:71], v[74:75], v[76:77], v[70:71]
	v_lshlrev_b32_e32 v74, 16, v23
	v_and_b32_e32 v75, 0xffff0000, v23
	v_pk_fma_f32 v[70:71], v[78:79], v[74:75], v[70:71]
	v_lshlrev_b32_e32 v74, 16, v27
	v_and_b32_e32 v75, 0xffff0000, v27
	v_pk_fma_f32 v[70:71], v[82:83], v[74:75], v[70:71]
	v_lshlrev_b32_e32 v74, 16, v31
	v_and_b32_e32 v75, 0xffff0000, v31
	v_pk_fma_f32 v[70:71], v[86:87], v[74:75], v[70:71]
	v_lshlrev_b32_e32 v74, 16, v21
	v_and_b32_e32 v75, 0xffff0000, v21
	v_pk_fma_f32 v[74:75], v[94:95], v[74:75], v[90:91]
	v_lshlrev_b32_e32 v76, 16, v25
	v_and_b32_e32 v77, 0xffff0000, v25
	v_pk_fma_f32 v[74:75], v[98:99], v[76:77], v[74:75]
	v_lshlrev_b32_e32 v76, 16, v29
	v_and_b32_e32 v77, 0xffff0000, v29
	v_pk_fma_f32 v[74:75], v[102:103], v[76:77], v[74:75]
	v_lshlrev_b32_e32 v76, 16, v33
	v_and_b32_e32 v77, 0xffff0000, v33
	v_readlane_b32 s57, v251, 13
	v_readlane_b32 s58, v251, 14
	v_readlane_b32 s59, v251, 15
	v_pk_fma_f32 v[74:75], v[106:107], v[76:77], v[74:75]
	ds_write_b128 v206, v[68:71] offset:16896
	ds_write_b128 v206, v[72:75] offset:16912
	s_cbranch_vccnz .LBB0_552
	s_lshl_b32 s4, s37, 7
	s_and_b32 s4, s4, 0x780
	v_or_b32_e32 v2, s4, v134
	s_lshl_b32 s4, s37, 2
	s_and_b32 s12, s4, 0xfc0
	v_mov_b32_e32 v4, v67
	v_mov_b32_e32 v5, v67
	v_add_u32_e32 v14, s12, v135
	v_lshlrev_b32_e32 v66, 1, v2
	v_mov_b32_e32 v2, v67
	v_mov_b32_e32 v3, v67
	v_mov_b64_e32 v[8:9], v[4:5]
	s_and_b32 s41, s4, 0xfffff000
	v_lshl_add_u64 v[30:31], s[0:1], 0, v[66:67]
	v_cmp_lt_i32_e32 vcc, -1, v14
	v_mov_b64_e32 v[6:7], v[2:3]
	s_and_saveexec_b64 s[4:5], vcc
	s_cbranch_execz .LBB0_545
	v_add_u32_e32 v6, s41, v14
	v_ashrrev_i32_e32 v7, 31, v6
	v_lshlrev_b64 v[6:7], 12, v[6:7]
	v_lshl_add_u64 v[6:7], v[30:31], 0, v[6:7]
	global_load_dwordx4 v[6:9], v[6:7], off
